# NA-in GEMM: unit-to-workgroup permutation so the slow V^T column tiles are spread two per workgroup over 128 workgroups without tail units (was four each on 64), tail V^T units exchanged with fast uni
# baseline (speedup 1.0000x reference)
; __device__ __forceinline__ unsigned pk2(float lo, float hi) { unsigned r; asm("v_cvt_pk_bf16_f32 %0, %1, %2" : "=v"(r) : "v"(lo), "v"(hi)); return r; }
;     __device__ __forceinline__ bool next(int i, Unit& u) const {
;         const int L = i * G + (((i + 1) * G <= n) ? c : cp); if (L >= n) return false;
;         if (mode == 0) { u.pm = L / nN; u.pn = L - u.pm * nN; }
;     __device__ __forceinline__ void operator()(const pg8::Unit& u, int rl, int cl, f32x4 v0, f32x4 v1) const {
;         const int sel = u.pn >> 2, col = (u.pn & 3) * 256 + cl; const size_t row = (size_t)u.pm * 256 + rl;
;         if (sel == 2) {
;             const int b = u.pm / 17, t = (u.pm - 17 * b) * 256 + rl, head = col >> 6, d = col & 63;
;             bf16* p = vt + ((size_t)(b * 16 + head) * 64 + d) * TB + t;
;             const unsigned w0 = pk2(v0.x, v0.y), w1 = pk2(v0.z, v0.w), w2 = pk2(v1.x, v1.y), w3 = pk2(v1.z, v1.w);
;             p[0] = (bf16)w0; p[TB] = (bf16)(w0 >> 16); p[2 * TB] = (bf16)w1; p[3 * TB] = (bf16)(w1 >> 16);
;             p[4 * TB] = (bf16)w2; p[5 * TB] = (bf16)(w2 >> 16); p[6 * TB] = (bf16)w3; p[7 * TB] = (bf16)(w3 >> 16);
.LBB0_926:
	s_add_i32 s60, s60, 1
	s_mul_i32 s7, s60, s30
	s_add_i32 s17, s7, s30
	s_cmpk_gt_i32 s17, 0x440
	s_cselect_b32 s17, s2, s3
	s_cbranch_scc1 .Lnai_part
	s_cmp_lt_u32 s60, 2
	s_cbranch_scc1 .Lnai_part
	s_add_i32 s17, s17, 12
	s_and_b32 s17, s17, 0xff
.Lnai_part:
	s_add_i32 s7, s17, s7
	s_add_i32 s94, s7, 0xfffffbf8
	s_and_b32 s95, s94, 0xffffffcc
	s_cmp_eq_u32 s95, 0
	s_cbranch_scc0 .Lnai_not1
	s_and_b32 s95, s94, 0x30
	s_add_i32 s7, s7, s95
	s_addk_i32 s7, 0xff14
	s_branch .Lnai_done
.Lnai_not1:
	s_add_i32 s94, s7, 0xfffffce4
	s_and_b32 s95, s94, 0xffffff9c
	s_cmp_eq_u32 s95, 0
	s_cbranch_scc0 .Lnai_done
	s_and_b32 s95, s94, 0x60
	s_lshr_b32 s95, s95, 1
	s_and_b32 s94, s94, 3
	s_add_i32 s7, s95, s94
	s_addk_i32 s7, 0x408
.Lnai_done:
	s_cmpk_lt_i32 s7, 0x440
	s_cselect_b64 s[22:23], -1, 0
	s_cmpk_gt_i32 s7, 0x43f
	s_cbranch_scc1 .LBB0_928
	s_ashr_i32 s16, s7, 31
	s_lshr_b32 s16, s16, 28
	s_add_i32 s17, s7, s16
	s_ashr_i32 s16, s17, 4
	s_and_b32 s17, s17, -16
	s_sub_i32 s18, s7, s17
